# seam2: waiting workgroups of a batch-group barrier poll the arrival counter directly (one fewer serial atomic hop per seam) when the group sits on one XCC
# speedup vs baseline: 1.0043x; 1.0043x over previous
.LBB0_462:
	s_lshl_b32 s0, s4, 8
	s_add_u32 s36, s44, s0
	s_addc_u32 s4, s45, 0
	v_mov_b32_e32 v3, s36
	v_add_co_u32_e32 v4, vcc, 0x1000, v3
	v_mov_b32_e32 v3, s4
	s_nop 0
	v_addc_co_u32_e32 v5, vcc, 0, v3, vcc
	flat_atomic_add v4, v[4:5], v200 offset:1024 sc0
	v_cvt_f32_u32_e32 v3, v2
	v_sub_u32_e32 v5, 0, v2
	v_rcp_iflag_f32_e32 v3, v3
	s_nop 0
	v_mul_f32_e32 v3, 0x4f7ffffe, v3
	v_cvt_u32_f32_e32 v3, v3
	v_mul_lo_u32 v5, v5, v3
	v_mul_hi_u32 v5, v3, v5
	v_add_u32_e32 v3, v3, v5
	s_waitcnt vmcnt(0) lgkmcnt(0)
	v_mul_hi_u32 v3, v4, v3
	v_mul_lo_u32 v5, v3, v2
	v_sub_u32_e32 v5, v4, v5
	v_cmp_ge_u32_e32 vcc, v5, v2
	v_add_u32_e32 v6, 1, v3
	s_nop 0
	v_cndmask_b32_e32 v3, v3, v6, vcc
	v_sub_u32_e32 v6, v5, v2
	v_cndmask_b32_e32 v5, v5, v6, vcc
	v_cmp_ge_u32_e32 vcc, v5, v2
	v_add_u32_e32 v5, 1, v3
	v_add_u32_e32 v6, 1, v4
	v_cndmask_b32_e32 v3, v3, v5, vcc
	v_mad_u64_u32 v[4:5], s[0:1], v2, v3, v[2:3]
	v_cmp_ne_u32_e32 vcc, v6, v4
	s_and_saveexec_b64 s[0:1], vcc
	s_xor_b64 s[0:1], exec, s[0:1]
	s_cbranch_execz .LBB0_475
	v_cmp_lt_u32_e32 vcc, 1, v0
	v_add_u32_e32 v6, 1, v3
	v_mov_b32_e32 v7, 0x2000
	v_cndmask_b32_e32 v3, v4, v6, vcc
	v_mov_b32_e32 v6, 0x1000
	s_nop 0
	v_cndmask_b32_e32 v6, v6, v7, vcc
	v_mov_b32_e32 v0, s36
	s_nop 0
	v_add_co_u32_e32 v4, vcc, v6, v0
	v_mov_b32_e32 v0, s4
	v_readfirstlane_b32 s16, v6
	v_addc_co_u32_e32 v5, vcc, 0, v0, vcc
	flat_load_dword v0, v[4:5] offset:1024 sc1
	s_add_u32 s16, s16, 0x400
	s_add_u32 s16, s36, s16
	s_addc_u32 s17, s4, 0
	s_waitcnt vmcnt(0) lgkmcnt(0)
	v_cmp_lt_u32_e32 vcc, v0, v3
	s_and_saveexec_b64 s[14:15], vcc
	s_cbranch_execz .LBB0_474
	s_mov_b32 s34, 1
	s_mov_b64 s[18:19], 0
	s_branch .LBB0_466

.LBB0_470:
	s_andn2_b64 s[22:23], s[22:23], exec
	s_and_b64 s[28:29], s[28:29], exec
	s_or_b64 s[22:23], s[22:23], s[28:29]
	s_and_saveexec_b64 s[28:29], s[26:27]
	s_cbranch_execz .LBB0_465
	v_mov_b64_e32 v[4:5], s[16:17]
	flat_load_dword v0, v[4:5] sc1
	s_add_i32 s34, s34, 1
	s_or_b64 s[22:23], s[22:23], exec
	s_waitcnt vmcnt(0) lgkmcnt(0)
	v_cmp_ge_u32_e32 vcc, v0, v3
	s_orn2_b64 s[24:25], vcc, exec
	s_branch .LBB0_465

.LBB0_642:
	s_lshl_b32 s0, s4, 8
	s_add_u32 s36, s14, s0
	s_addc_u32 s4, s15, 0
	v_mov_b32_e32 v3, s36
	v_add_co_u32_e32 v4, vcc, 0x1000, v3
	v_mov_b32_e32 v3, s4
	s_nop 0
	v_addc_co_u32_e32 v5, vcc, 0, v3, vcc
	flat_atomic_add v4, v[4:5], v200 offset:1024 sc0
	v_cvt_f32_u32_e32 v3, v2
	v_sub_u32_e32 v5, 0, v2
	v_rcp_iflag_f32_e32 v3, v3
	s_nop 0
	v_mul_f32_e32 v3, 0x4f7ffffe, v3
	v_cvt_u32_f32_e32 v3, v3
	v_mul_lo_u32 v5, v5, v3
	v_mul_hi_u32 v5, v3, v5
	v_add_u32_e32 v3, v3, v5
	s_waitcnt vmcnt(0) lgkmcnt(0)
	v_mul_hi_u32 v3, v4, v3
	v_mul_lo_u32 v5, v3, v2
	v_sub_u32_e32 v5, v4, v5
	v_cmp_ge_u32_e32 vcc, v5, v2
	v_add_u32_e32 v6, 1, v3
	s_nop 0
	v_cndmask_b32_e32 v3, v3, v6, vcc
	v_sub_u32_e32 v6, v5, v2
	v_cndmask_b32_e32 v5, v5, v6, vcc
	v_cmp_ge_u32_e32 vcc, v5, v2
	v_add_u32_e32 v5, 1, v3
	v_add_u32_e32 v6, 1, v4
	v_cndmask_b32_e32 v3, v3, v5, vcc
	v_mad_u64_u32 v[4:5], s[0:1], v2, v3, v[2:3]
	v_cmp_ne_u32_e32 vcc, v6, v4
	s_and_saveexec_b64 s[0:1], vcc
	s_xor_b64 s[0:1], exec, s[0:1]
	s_cbranch_execz .LBB0_655
	v_cmp_lt_u32_e32 vcc, 1, v0
	v_add_u32_e32 v6, 1, v3
	v_mov_b32_e32 v7, 0x2000
	v_cndmask_b32_e32 v3, v4, v6, vcc
	v_mov_b32_e32 v6, 0x1000
	s_nop 0
	v_cndmask_b32_e32 v6, v6, v7, vcc
	v_mov_b32_e32 v0, s36
	s_nop 0
	v_add_co_u32_e32 v4, vcc, v6, v0
	v_mov_b32_e32 v0, s4
	v_readfirstlane_b32 s18, v6
	v_addc_co_u32_e32 v5, vcc, 0, v0, vcc
	flat_load_dword v0, v[4:5] offset:1024 sc1
	s_add_u32 s18, s18, 0x400
	s_add_u32 s18, s36, s18
	s_addc_u32 s19, s4, 0
	s_waitcnt vmcnt(0) lgkmcnt(0)
	v_cmp_lt_u32_e32 vcc, v0, v3
	s_and_saveexec_b64 s[16:17], vcc
	s_cbranch_execz .LBB0_654
	s_mov_b32 s37, 1
	s_mov_b64 s[20:21], 0
	s_branch .LBB0_646

.LBB0_650:
	s_andn2_b64 s[24:25], s[24:25], exec
	s_and_b64 s[30:31], s[30:31], exec
	s_or_b64 s[24:25], s[24:25], s[30:31]
	s_and_saveexec_b64 s[30:31], s[28:29]
	s_cbranch_execz .LBB0_645
	v_mov_b64_e32 v[4:5], s[18:19]
	flat_load_dword v0, v[4:5] sc1
	s_add_i32 s37, s37, 1
	s_or_b64 s[24:25], s[24:25], exec
	s_waitcnt vmcnt(0) lgkmcnt(0)
	v_cmp_ge_u32_e32 vcc, v0, v3
	s_orn2_b64 s[26:27], vcc, exec
	s_branch .LBB0_645

.LBB0_1265:
	s_lshl_b32 s0, s4, 8
	s_add_u32 s38, s46, s0
	s_addc_u32 s4, s47, 0
	v_mov_b32_e32 v3, s38
	v_add_co_u32_e32 v4, vcc, 0x1000, v3
	v_mov_b32_e32 v3, s4
	s_nop 0
	v_addc_co_u32_e32 v5, vcc, 0, v3, vcc
	flat_atomic_add v4, v[4:5], v200 offset:1024 sc0
	v_cvt_f32_u32_e32 v3, v2
	v_sub_u32_e32 v5, 0, v2
	v_rcp_iflag_f32_e32 v3, v3
	s_nop 0
	v_mul_f32_e32 v3, 0x4f7ffffe, v3
	v_cvt_u32_f32_e32 v3, v3
	v_mul_lo_u32 v5, v5, v3
	v_mul_hi_u32 v5, v3, v5
	v_add_u32_e32 v3, v3, v5
	s_waitcnt vmcnt(0) lgkmcnt(0)
	v_mul_hi_u32 v3, v4, v3
	v_mul_lo_u32 v5, v3, v2
	v_sub_u32_e32 v5, v4, v5
	v_cmp_ge_u32_e32 vcc, v5, v2
	v_add_u32_e32 v6, 1, v3
	s_nop 0
	v_cndmask_b32_e32 v3, v3, v6, vcc
	v_sub_u32_e32 v6, v5, v2
	v_cndmask_b32_e32 v5, v5, v6, vcc
	v_cmp_ge_u32_e32 vcc, v5, v2
	v_add_u32_e32 v5, 1, v3
	v_add_u32_e32 v6, 1, v4
	v_cndmask_b32_e32 v3, v3, v5, vcc
	v_mad_u64_u32 v[4:5], s[0:1], v2, v3, v[2:3]
	v_cmp_ne_u32_e32 vcc, v6, v4
	s_and_saveexec_b64 s[0:1], vcc
	s_xor_b64 s[0:1], exec, s[0:1]
	s_cbranch_execz .LBB0_1278
	v_cmp_lt_u32_e32 vcc, 1, v0
	v_add_u32_e32 v6, 1, v3
	v_mov_b32_e32 v7, 0x2000
	v_cndmask_b32_e32 v3, v4, v6, vcc
	v_mov_b32_e32 v6, 0x1000
	s_nop 0
	v_cndmask_b32_e32 v6, v6, v7, vcc
	v_mov_b32_e32 v0, s38
	s_nop 0
	v_add_co_u32_e32 v4, vcc, v6, v0
	v_mov_b32_e32 v0, s4
	v_readfirstlane_b32 s18, v6
	v_addc_co_u32_e32 v5, vcc, 0, v0, vcc
	flat_load_dword v0, v[4:5] offset:1024 sc1
	s_add_u32 s18, s18, 0x400
	s_add_u32 s18, s38, s18
	s_addc_u32 s19, s4, 0
	s_waitcnt vmcnt(0) lgkmcnt(0)
	v_cmp_lt_u32_e32 vcc, v0, v3
	s_and_saveexec_b64 s[16:17], vcc
	s_cbranch_execz .LBB0_1277
	s_mov_b32 s36, 1
	s_mov_b64 s[20:21], 0
	s_branch .LBB0_1269

.LBB0_1273:
	s_andn2_b64 s[24:25], s[24:25], exec
	s_and_b64 s[30:31], s[30:31], exec
	s_or_b64 s[24:25], s[24:25], s[30:31]
	s_and_saveexec_b64 s[30:31], s[28:29]
	s_cbranch_execz .LBB0_1268
	v_mov_b64_e32 v[4:5], s[18:19]
	flat_load_dword v0, v[4:5] sc1
	s_add_i32 s36, s36, 1
	s_or_b64 s[24:25], s[24:25], exec
	s_waitcnt vmcnt(0) lgkmcnt(0)
	v_cmp_ge_u32_e32 vcc, v0, v3
	s_orn2_b64 s[26:27], vcc, exec
	s_branch .LBB0_1268

.LBB0_1414:
	s_lshl_b32 s0, s4, 8
	s_add_u32 s36, s48, s0
	s_addc_u32 s4, s49, 0
	v_mov_b32_e32 v3, s36
	v_add_co_u32_e32 v4, vcc, 0x1000, v3
	v_mov_b32_e32 v3, s4
	s_nop 0
	v_addc_co_u32_e32 v5, vcc, 0, v3, vcc
	flat_atomic_add v4, v[4:5], v200 offset:1024 sc0
	v_cvt_f32_u32_e32 v3, v2
	v_sub_u32_e32 v5, 0, v2
	v_rcp_iflag_f32_e32 v3, v3
	s_nop 0
	v_mul_f32_e32 v3, 0x4f7ffffe, v3
	v_cvt_u32_f32_e32 v3, v3
	v_mul_lo_u32 v5, v5, v3
	v_mul_hi_u32 v5, v3, v5
	v_add_u32_e32 v3, v3, v5
	s_waitcnt vmcnt(0) lgkmcnt(0)
	v_mul_hi_u32 v3, v4, v3
	v_mul_lo_u32 v5, v3, v2
	v_sub_u32_e32 v5, v4, v5
	v_cmp_ge_u32_e32 vcc, v5, v2
	v_add_u32_e32 v6, 1, v3
	s_nop 0
	v_cndmask_b32_e32 v3, v3, v6, vcc
	v_sub_u32_e32 v6, v5, v2
	v_cndmask_b32_e32 v5, v5, v6, vcc
	v_cmp_ge_u32_e32 vcc, v5, v2
	v_add_u32_e32 v5, 1, v3
	v_add_u32_e32 v6, 1, v4
	v_cndmask_b32_e32 v3, v3, v5, vcc
	v_mad_u64_u32 v[4:5], s[0:1], v2, v3, v[2:3]
	v_cmp_ne_u32_e32 vcc, v6, v4
	s_and_saveexec_b64 s[0:1], vcc
	s_xor_b64 s[0:1], exec, s[0:1]
	s_cbranch_execz .LBB0_1427
	v_cmp_lt_u32_e32 vcc, 1, v0
	v_add_u32_e32 v6, 1, v3
	v_mov_b32_e32 v7, 0x2000
	v_cndmask_b32_e32 v3, v4, v6, vcc
	v_mov_b32_e32 v6, 0x1000
	s_nop 0
	v_cndmask_b32_e32 v6, v6, v7, vcc
	v_mov_b32_e32 v0, s36
	s_nop 0
	v_add_co_u32_e32 v4, vcc, v6, v0
	v_mov_b32_e32 v0, s4
	v_readfirstlane_b32 s16, v6
	v_addc_co_u32_e32 v5, vcc, 0, v0, vcc
	flat_load_dword v0, v[4:5] offset:1024 sc1
	s_add_u32 s16, s16, 0x400
	s_add_u32 s16, s36, s16
	s_addc_u32 s17, s4, 0
	s_waitcnt vmcnt(0) lgkmcnt(0)
	v_cmp_lt_u32_e32 vcc, v0, v3
	s_and_saveexec_b64 s[12:13], vcc
	s_cbranch_execz .LBB0_1426
	s_mov_b32 s34, 1
	s_mov_b64 s[18:19], 0
	s_branch .LBB0_1418

.LBB0_1589:
	s_lshl_b32 s0, s4, 8
	s_add_u32 s34, s44, s0
	s_addc_u32 s4, s45, 0
	v_mov_b32_e32 v3, s34
	v_add_co_u32_e32 v4, vcc, 0x1000, v3
	v_mov_b32_e32 v3, s4
	s_nop 0
	v_addc_co_u32_e32 v5, vcc, 0, v3, vcc
	flat_atomic_add v4, v[4:5], v200 offset:1024 sc0
	v_cvt_f32_u32_e32 v3, v2
	v_sub_u32_e32 v5, 0, v2
	v_rcp_iflag_f32_e32 v3, v3
	s_nop 0
	v_mul_f32_e32 v3, 0x4f7ffffe, v3
	v_cvt_u32_f32_e32 v3, v3
	v_mul_lo_u32 v5, v5, v3
	v_mul_hi_u32 v5, v3, v5
	v_add_u32_e32 v3, v3, v5
	s_waitcnt vmcnt(0) lgkmcnt(0)
	v_mul_hi_u32 v3, v4, v3
	v_mul_lo_u32 v5, v3, v2
	v_sub_u32_e32 v5, v4, v5
	v_cmp_ge_u32_e32 vcc, v5, v2
	v_add_u32_e32 v6, 1, v3
	s_nop 0
	v_cndmask_b32_e32 v3, v3, v6, vcc
	v_sub_u32_e32 v6, v5, v2
	v_cndmask_b32_e32 v5, v5, v6, vcc
	v_cmp_ge_u32_e32 vcc, v5, v2
	v_add_u32_e32 v5, 1, v3
	v_add_u32_e32 v6, 1, v4
	v_cndmask_b32_e32 v3, v3, v5, vcc
	v_mad_u64_u32 v[4:5], s[0:1], v2, v3, v[2:3]
	v_cmp_ne_u32_e32 vcc, v6, v4
	s_and_saveexec_b64 s[0:1], vcc
	s_xor_b64 s[0:1], exec, s[0:1]
	s_cbranch_execz .LBB0_1602
	v_cmp_lt_u32_e32 vcc, 1, v0
	v_add_u32_e32 v6, 1, v3
	v_mov_b32_e32 v7, 0x2000
	v_cndmask_b32_e32 v3, v4, v6, vcc
	v_mov_b32_e32 v6, 0x1000
	s_nop 0
	v_cndmask_b32_e32 v6, v6, v7, vcc
	v_mov_b32_e32 v0, s34
	s_nop 0
	v_add_co_u32_e32 v4, vcc, v6, v0
	v_mov_b32_e32 v0, s4
	v_readfirstlane_b32 s14, v6
	v_addc_co_u32_e32 v5, vcc, 0, v0, vcc
	flat_load_dword v0, v[4:5] offset:1024 sc1
	s_add_u32 s14, s14, 0x400
	s_add_u32 s14, s34, s14
	s_addc_u32 s15, s4, 0
	s_waitcnt vmcnt(0) lgkmcnt(0)
	v_cmp_lt_u32_e32 vcc, v0, v3
	s_and_saveexec_b64 s[12:13], vcc
	s_cbranch_execz .LBB0_1601
	s_mov_b32 s30, 1
	s_mov_b64 s[16:17], 0
	s_branch .LBB0_1593

.LBB0_1597:
	s_andn2_b64 s[20:21], s[20:21], exec
	s_and_b64 s[26:27], s[26:27], exec
	s_or_b64 s[20:21], s[20:21], s[26:27]
	s_and_saveexec_b64 s[26:27], s[24:25]
	s_cbranch_execz .LBB0_1592
	v_mov_b64_e32 v[4:5], s[14:15]
	flat_load_dword v0, v[4:5] sc1
	s_add_i32 s30, s30, 1
	s_or_b64 s[20:21], s[20:21], exec
	s_waitcnt vmcnt(0) lgkmcnt(0)
	v_cmp_ge_u32_e32 vcc, v0, v3
	s_orn2_b64 s[22:23], vcc, exec
	s_branch .LBB0_1592
